# attention phase: K/V tile rows in LDS padded to 160 B instead of 144 B (bank-conflict-free row reads and transposed reads)
# baseline (speedup 1.0000x reference)
.LBB0_365:
	s_cmp_lt_i32 s90, 4
	v_writelane_b32 v251, s88, 44
	s_cselect_b64 s[2:3], -1, 0
	s_and_b64 s[2:3], s[2:3], s[0:1]
	v_writelane_b32 v251, s89, 45
	v_writelane_b32 v251, s90, 46
	v_writelane_b32 v251, s91, 47
	v_writelane_b32 v251, s58, 48
	v_writelane_b32 v251, s69, 49
	v_writelane_b32 v251, s64, 50
	s_andn2_b64 vcc, exec, s[2:3]
	s_nop 0
	v_writelane_b32 v251, s65, 51
	v_writelane_b32 v251, s72, 52
	s_nop 1
	v_writelane_b32 v251, s73, 53
	v_writelane_b32 v251, s74, 54
	v_writelane_b32 v251, s75, 55
	v_writelane_b32 v251, s76, 56
	v_writelane_b32 v251, s77, 57
	v_writelane_b32 v251, s78, 58
	v_writelane_b32 v251, s79, 59
	v_writelane_b32 v251, s80, 60
	v_writelane_b32 v250, s84, 0
	v_writelane_b32 v251, s81, 61
	v_writelane_b32 v250, s85, 1
	v_writelane_b32 v251, s82, 62
	v_writelane_b32 v250, s86, 2
	v_writelane_b32 v251, s83, 63
	v_writelane_b32 v250, s87, 3
	s_cbranch_vccnz .LBB0_425
	v_writelane_b32 v250, s2, 4
	s_cmpk_gt_i32 s58, 0x23f
	s_nop 0
	v_writelane_b32 v250, s3, 5
	v_writelane_b32 v250, s62, 6
	s_nop 1
	v_writelane_b32 v250, s63, 7
	v_writelane_b32 v250, s59, 8
	v_writelane_b32 v250, s60, 9
	s_nop 1
	v_writelane_b32 v250, s61, 10
	s_cbranch_scc1 .LBB0_424
	v_bfe_u32 v3, v0, 4, 2
	v_lshlrev_b32_e32 v192, 2, v3
	s_movk_i32 s0, 0xa0
	v_mov_b32_e32 v8, 0x1400
	v_mad_u32_u24 v217, v186, s0, v8
	v_or_b32_e32 v8, 1, v192
	v_or_b32_e32 v9, 18, v192
	s_waitcnt vmcnt(0)
	v_or_b32_e32 v11, 16, v186
	v_lshrrev_b32_e32 v187, 3, v0
	v_lshlrev_b32_e32 v2, 3, v0
	v_or_b32_e32 v7, 32, v186
	v_cmp_ge_u32_e64 s[8:9], v8, v186
	v_or_b32_e32 v8, 2, v192
	v_cmp_ge_u32_e64 s[24:25], v9, v11
	v_cmp_le_u32_e64 s[26:27], v9, v11
	v_or_b32_e32 v9, 33, v192
	v_and_b32_e32 v2, 56, v2
	v_mul_u32_u24_e32 v4, 0x50, v187
	v_cmp_ge_u32_e64 s[12:13], v8, v186
	v_cmp_le_u32_e64 s[14:15], v8, v186
	v_or_b32_e32 v8, 3, v192
	v_cmp_ge_u32_e64 s[34:35], v9, v7
	v_cmp_le_u32_e64 s[36:37], v9, v7
	v_or_b32_e32 v9, 34, v192
	v_lshlrev_b32_e32 v5, 1, v4
	v_lshlrev_b32_e32 v4, 1, v2
	v_cmp_ge_u32_e64 s[16:17], v8, v186
	v_cmp_le_u32_e64 s[18:19], v8, v186
	v_or_b32_e32 v8, 17, v192
	v_cmp_ge_u32_e64 s[38:39], v9, v7
	v_cmp_le_u32_e64 s[40:41], v9, v7
	v_or_b32_e32 v9, 35, v192
	s_brev_b32 s92, 1
	v_lshlrev_b32_e32 v6, 3, v3
	v_lshlrev_b32_e32 v188, 4, v3
	v_add3_u32 v193, 0, v5, v4
	v_cmp_eq_u32_e64 s[60:61], 0, v3
	v_bfe_u32 v3, v0, 2, 2
	v_lshlrev_b32_e32 v5, 2, v0
	v_cmp_ge_u32_e64 s[20:21], v8, v11
	v_cmp_le_u32_e64 s[22:23], v8, v11
	v_or_b32_e32 v8, 48, v186
	v_cmp_ge_u32_e64 s[42:43], v9, v7
	v_cmp_le_u32_e64 s[44:45], v9, v7
	v_or_b32_e32 v7, 49, v192
	s_mov_b32 s93, s92
	s_mov_b32 s94, s92
	s_mov_b32 s95, s92
	v_mov_b32_e32 v189, 0
	v_or_b32_e32 v3, v192, v3
	v_and_b32_e32 v5, 12, v5
	v_mul_u32_u24_e32 v216, 0xa0, v186
	v_cmp_ge_u32_e64 s[46:47], v7, v8
	v_cmp_le_u32_e64 s[48:49], v7, v8
	v_or_b32_e32 v7, 50, v192
	v_writelane_b32 v250, s92, 11
	v_or_b32_e32 v10, 19, v192
	v_cmp_ge_u32_e64 s[50:51], v7, v8
	v_cmp_le_u32_e64 s[52:53], v7, v8
	v_or_b32_e32 v7, 51, v192
	v_mul_u32_u24_e32 v218, 0xa0, v3
	v_add3_u32 v219, 0, v216, v188
	v_lshlrev_b32_e32 v221, 1, v5
	v_mov_b32_e32 v5, v189
	v_lshlrev_b32_e32 v196, 1, v2
	v_mbcnt_lo_u32_b32 v2, -1, 0
	v_writelane_b32 v250, s93, 12
	v_lshrrev_b32_e32 v1, 6, v0
	v_lshl_add_u64 v[190:191], s[96:97], 0, v[188:189]
	s_mov_b32 s75, 0
	s_movk_i32 s33, 0x1200
	v_cmp_ge_u32_e64 s[4:5], v192, v186
	v_cmp_le_u32_e64 s[6:7], v192, v186
	v_cmp_lt_u32_e64 s[10:11], v192, v186
	v_cmp_ge_u32_e64 s[28:29], v10, v11
	v_cmp_le_u32_e64 s[30:31], v10, v11
	v_cmp_ge_u32_e64 s[54:55], v7, v8
	v_cmp_le_u32_e64 s[56:57], v7, v8
	v_add_u32_e32 v220, 0x1400, v219
	v_add3_u32 v222, 0, v218, v221
	v_lshl_add_u64 v[194:195], s[96:97], 0, v[4:5]
	s_mov_b32 s58, 0xf149f2ca
	v_mbcnt_hi_u32_b32 v223, -1, v2
	v_lshlrev_b32_e32 v224, 1, v6
	v_mov_b32_e32 v225, 0xf149f2ca
	v_readlane_b32 s59, v251, 48
	v_writelane_b32 v250, s94, 13
	v_writelane_b32 v250, s95, 14
	s_branch .LBB0_369

.LBB0_380:
	v_add_u32_e32 v3, s62, v187
	v_mov_b64_e32 v[4:5], s[96:97]
	v_mad_i64_i32 v[4:5], s[0:1], v3, s33, v[4:5]
	s_lshl_b32 s74, s3, 7
	v_lshl_add_u64 v[4:5], v[4:5], 0, s[74:75]
	v_mov_b32_e32 v197, v189
	v_lshl_add_u64 v[8:9], v[4:5], 0, v[196:197]
	global_load_dwordx4 v[4:7], v[8:9], off offset:2048
	s_nop 0
	global_load_dwordx4 v[8:11], v[8:9], off offset:2304
	s_cmp_lt_i32 s64, 1
	s_mov_b64 s[0:1], -1
	s_barrier
	s_waitcnt vmcnt(1)
	ds_write_b128 v193, v[4:7]
	s_waitcnt vmcnt(0)
	ds_write_b128 v193, v[8:11] offset:10240
	s_cbranch_scc0 .LBB0_382
	s_lshl_b32 s0, s68, 8
	s_lshl_b32 s1, s64, 6
	s_sub_i32 s0, s0, s1
	s_add_i32 s62, s0, 0x4000
	s_mov_b64 s[0:1], 0

.LBB0_384:
	s_lshl_b32 s3, s3, 6
	v_add_u32_e32 v3, s62, v187
	v_mov_b64_e32 v[4:5], s[96:97]
	v_mad_i64_i32 v[4:5], s[0:1], v3, s33, v[4:5]
	s_lshl_b32 s74, s3, 1
	v_lshl_add_u64 v[4:5], v[4:5], 0, s[74:75]
	v_mov_b32_e32 v197, v189
	v_lshl_add_u64 v[4:5], v[4:5], 0, v[196:197]
	global_load_dwordx4 v[66:69], v[4:5], off offset:2048
	global_load_dwordx4 v[70:73], v[4:5], off offset:2304
	s_cmp_gt_i32 s64, -3
	s_cselect_b64 s[0:1], -1, 0
	s_cmp_lt_i32 s64, -2
	s_waitcnt vmcnt(1)
	ds_write_b128 v193, v[66:69] offset:20480
	s_waitcnt vmcnt(0)
	ds_write_b128 v193, v[70:73] offset:30720
	s_cbranch_scc1 .LBB0_390
	s_cmp_lt_i32 s64, 2
	s_mov_b64 s[62:63], -1
	s_cbranch_scc0 .LBB0_387
	s_lshl_b32 s3, s68, 8
	s_lshl_b32 s62, s64, 6
	s_sub_i32 s3, s3, s62
	s_addk_i32 s3, 0x4040
	s_mov_b64 s[62:63], 0

.LBB0_390:
	s_cmpk_lt_u32 s69, 0x100
	v_lshlrev_b32_e32 v229, 6, v2
	s_cselect_b64 s[66:67], -1, 0
	s_lshl_b32 s3, s68, 11
	s_add_i32 s65, s2, s65
	s_lshl_b32 s68, s68, 8
	v_cndmask_b32_e64 v2, 0, 1, s[0:1]
	v_ashrrev_i32_e32 v205, 31, v204
	v_mad_i64_i32 v[212:213], s[62:63], v204, s33, 0
	v_ashrrev_i32_e32 v203, 31, v202
	v_mad_i64_i32 v[210:211], s[62:63], v202, s33, 0
	v_ashrrev_i32_e32 v201, 31, v200
	v_mad_i64_i32 v[208:209], s[62:63], v200, s33, 0
	v_ashrrev_i32_e32 v199, 31, v198
	v_mad_i64_i32 v[206:207], s[62:63], v198, s33, 0
	s_cmpk_gt_u32 s69, 0xff
	v_cmp_ne_u32_e64 s[0:1], 1, v2
	s_waitcnt lgkmcnt(0)
	s_barrier
	s_cbranch_scc1 .LBB0_398
	s_waitcnt lgkmcnt(0)
	s_barrier
	s_and_b64 vcc, exec, s[0:1]
	s_cbranch_vccnz .LBB0_398
	s_cmp_eq_u32 s64, -2
	s_waitcnt vmcnt(1)
	ds_write_b128 v193, v[66:69] offset:40960
	s_waitcnt vmcnt(0)
	ds_write_b128 v193, v[70:73] offset:51200
	s_cbranch_scc1 .LBB0_398
	s_cmp_lt_i32 s64, 3
	s_mov_b64 s[62:63], -1
	s_cbranch_scc1 .LBB0_395
	s_lshl_b32 s62, s65, 6
	s_add_i32 s62, s62, s3
	s_add_i32 s71, s62, 64
	s_mov_b64 s[62:63], 0

.LBB0_398:
	ds_read_b128 v[62:65], v219
	ds_read_b128 v[58:61], v219 offset:64
	ds_read_b128 v[50:53], v219 offset:2560
	ds_read_b128 v[54:57], v219 offset:2624
	v_mov_b64_e32 v[86:87], s[92:93]
	v_mov_b64_e32 v[88:89], s[94:95]
	ds_read_b128 v[10:13], v220
	ds_read_b128 v[14:17], v220 offset:64
	s_waitcnt lgkmcnt(5)
	v_mfma_f32_16x16x32_bf16 v[2:5], v[62:65], v[18:21], v[86:89]
	s_cmp_lt_i32 s64, 0
	s_cselect_b64 s[62:63], -1, 0
	s_cmp_lg_u32 s2, 0
	s_waitcnt lgkmcnt(4)
	v_mfma_f32_16x16x32_bf16 v[90:93], v[58:61], v[22:25], v[2:5]
	s_cselect_b64 s[72:73], -1, 0
	s_or_b64 s[62:63], s[62:63], s[72:73]
	s_and_b64 vcc, exec, s[62:63]
	s_waitcnt lgkmcnt(3)
	v_mfma_f32_16x16x32_bf16 v[2:5], v[50:53], v[18:21], v[86:89]
	s_waitcnt lgkmcnt(2)
	v_mfma_f32_16x16x32_bf16 v[94:97], v[54:57], v[22:25], v[2:5]
	v_mfma_f32_16x16x32_bf16 v[2:5], v[50:53], v[26:29], v[86:89]
	v_mfma_f32_16x16x32_bf16 v[6:9], v[62:65], v[26:29], v[86:89]
	v_mfma_f32_16x16x32_bf16 v[78:81], v[54:57], v[30:33], v[2:5]
	s_waitcnt lgkmcnt(1)
	v_mfma_f32_16x16x32_bf16 v[2:5], v[10:13], v[18:21], v[86:89]
	v_mfma_f32_16x16x32_bf16 v[74:77], v[58:61], v[30:33], v[6:9]
	s_waitcnt lgkmcnt(0)
	v_mfma_f32_16x16x32_bf16 v[98:101], v[14:17], v[22:25], v[2:5]
	s_nop 1
	ds_read_b128 v[6:9], v219 offset:7680
	v_mfma_f32_16x16x32_bf16 v[2:5], v[10:13], v[26:29], v[86:89]
	v_mfma_f32_16x16x32_bf16 v[82:85], v[14:17], v[30:33], v[2:5]
	s_nop 6
	ds_read_b128 v[2:5], v219 offset:7744
	s_waitcnt lgkmcnt(1)
	v_mfma_f32_16x16x32_bf16 v[102:105], v[6:9], v[18:21], v[86:89]
	v_mfma_f32_16x16x32_bf16 v[86:89], v[6:9], v[26:29], v[86:89]
	s_waitcnt lgkmcnt(0)
	v_mfma_f32_16x16x32_bf16 v[102:105], v[2:5], v[22:25], v[102:105]
	v_mfma_f32_16x16x32_bf16 v[86:89], v[2:5], v[30:33], v[86:89]
	s_cbranch_vccnz .LBB0_400
	v_mov_b32_e32 v74, s58
	v_cndmask_b32_e64 v90, v74, v90, s[4:5]
	v_cndmask_b32_e64 v78, v74, v78, s[4:5]
	v_mov_b32_e32 v74, 0xf149f2ca
	v_cndmask_b32_e64 v91, v225, v91, s[8:9]
	v_cndmask_b32_e64 v92, v225, v92, s[12:13]
	v_cndmask_b32_e64 v93, v225, v93, s[16:17]
	v_cndmask_b32_e64 v79, v225, v79, s[20:21]
	v_cndmask_b32_e64 v80, v225, v80, s[24:25]
	v_cndmask_b32_e64 v81, v225, v81, s[28:29]
	v_mov_b32_e32 v75, v74
	v_mov_b32_e32 v76, v74
	v_mov_b32_e32 v77, v74

.LBB0_402:
	s_nop 4
	v_max3_f32 v6, v74, s58, v75
	v_max3_f32 v6, v6, v76, v77
	v_max3_f32 v6, v6, v62, v63
	v_max3_f32 v6, v6, v64, v65
	v_max3_f32 v6, v6, v54, v55
	v_max3_f32 v6, v6, v56, v57
	v_max3_f32 v6, v6, v14, v15
	v_max3_f32 v6, v6, v16, v17
	ds_bpermute_b32 v7, v227, v6
	s_and_b32 s62, s69, 0xffffff00
	s_cmpk_eq_i32 s62, 0x100
	s_cselect_b64 s[94:95], -1, 0
	s_cmpk_lg_i32 s62, 0x100
	s_waitcnt lgkmcnt(0)
	v_max_f32_e32 v7, v7, v7
	v_max_f32_e32 v6, v6, v7
	ds_bpermute_b32 v7, v226, v6
	s_waitcnt lgkmcnt(0)
	v_max3_f32 v124, v6, v7, v118
	v_sub_f32_e32 v6, v74, v124
	v_exp_f32_e32 v6, v6
	v_sub_f32_e32 v7, v75, v124
	v_exp_f32_e32 v7, v7
	v_sub_f32_e32 v8, v76, v124
	v_sub_f32_e32 v101, v14, v124
	v_sub_f32_e32 v14, v62, v124
	v_add_f32_e32 v62, 0, v6
	v_exp_f32_e32 v8, v8
	v_sub_f32_e32 v9, v77, v124
	v_exp_f32_e32 v9, v9
	v_add_f32_e32 v62, v7, v62
	v_exp_f32_e32 v14, v14
	v_add_f32_e32 v62, v8, v62
	v_sub_f32_e32 v100, v15, v124
	v_sub_f32_e32 v15, v63, v124
	v_exp_f32_e32 v15, v15
	v_add_f32_e32 v62, v9, v62
	v_sub_f32_e32 v98, v17, v124
	v_sub_f32_e32 v99, v16, v124
	v_sub_f32_e32 v17, v65, v124
	v_sub_f32_e32 v16, v64, v124
	v_max3_f32 v65, v58, s58, v59
	v_add_f32_e32 v62, v14, v62
	v_exp_f32_e32 v16, v16
	v_max3_f32 v65, v65, v60, v61
	v_max3_f32 v65, v65, v50, v51
	v_add_f32_e32 v62, v15, v62
	v_exp_f32_e32 v17, v17
	v_max3_f32 v65, v65, v52, v53
	v_sub_f32_e32 v54, v54, v124
	v_max3_f32 v65, v65, v10, v11
	v_add_f32_e32 v62, v16, v62
	v_exp_f32_e32 v54, v54
	v_max3_f32 v65, v65, v12, v13
	v_sub_f32_e32 v55, v55, v124
	v_max3_f32 v65, v65, v2, v3
	v_add_f32_e32 v62, v17, v62
	v_exp_f32_e32 v55, v55
	v_max3_f32 v74, v65, v4, v5
	v_sub_f32_e32 v56, v56, v124
	ds_bpermute_b32 v75, v227, v74
	v_add_f32_e32 v62, v54, v62
	v_exp_f32_e32 v56, v56
	v_sub_f32_e32 v57, v57, v124
	v_exp_f32_e32 v57, v57
	v_add_f32_e32 v62, v55, v62
	s_waitcnt lgkmcnt(0)
	v_max_f32_e32 v75, v75, v75
	v_add_f32_e32 v63, v56, v62
	v_exp_f32_e32 v62, v101
	v_max_f32_e32 v75, v74, v75
	v_add_f32_e32 v63, v57, v63
	ds_bpermute_b32 v77, v226, v75
	v_exp_f32_e32 v65, v98
	v_add_f32_e32 v64, v62, v63
	v_exp_f32_e32 v63, v100
	s_waitcnt lgkmcnt(0)
	v_max3_f32 v125, v75, v77, v118
	v_sub_f32_e32 v98, v2, v125
	v_add_f32_e32 v76, v63, v64
	v_exp_f32_e32 v64, v99
	v_sub_f32_e32 v2, v58, v125
	v_exp_f32_e32 v2, v2
	v_sub_f32_e32 v77, v3, v125
	v_sub_f32_e32 v3, v59, v125
	v_exp_f32_e32 v3, v3
	v_add_f32_e32 v74, v64, v76
	v_sub_f32_e32 v76, v4, v125
	v_sub_f32_e32 v4, v60, v125
	v_sub_f32_e32 v106, v10, v125
	v_sub_f32_e32 v10, v50, v125
	v_add_f32_e32 v50, 0, v2
	v_exp_f32_e32 v4, v4
	v_sub_f32_e32 v75, v5, v125
	v_sub_f32_e32 v5, v61, v125
	v_exp_f32_e32 v5, v5
	v_add_f32_e32 v50, v3, v50
	v_exp_f32_e32 v10, v10
	v_add_f32_e32 v50, v4, v50
	v_sub_f32_e32 v101, v11, v125
	v_sub_f32_e32 v11, v51, v125
	v_exp_f32_e32 v11, v11
	v_add_f32_e32 v50, v5, v50
	v_sub_f32_e32 v100, v12, v125
	v_sub_f32_e32 v12, v52, v125
	v_exp_f32_e32 v12, v12
	v_add_f32_e32 v50, v10, v50
	v_sub_f32_e32 v99, v13, v125
	v_sub_f32_e32 v13, v53, v125
	v_exp_f32_e32 v13, v13
	v_add_f32_e32 v50, v11, v50
	s_nop 0
	v_add_f32_e32 v51, v12, v50
	v_exp_f32_e32 v50, v106
	v_add_f32_e32 v74, v65, v74
	v_add_f32_e32 v52, v13, v51
	v_exp_f32_e32 v51, v101
	s_nop 0
	v_add_f32_e32 v53, v50, v52
	v_exp_f32_e32 v52, v100
	s_nop 0
	v_add_f32_e32 v58, v51, v53
	v_exp_f32_e32 v53, v99
	s_nop 0
	v_add_f32_e32 v59, v52, v58
	v_exp_f32_e32 v58, v98
	s_nop 0
	v_add_f32_e32 v60, v53, v59
	v_exp_f32_e32 v59, v77
	s_nop 0
	v_add_f32_e32 v61, v58, v60
	v_exp_f32_e32 v60, v76
	s_nop 0
	v_add_f32_e32 v76, v59, v61
	v_exp_f32_e32 v61, v75
	s_nop 0
	v_add_f32_e32 v75, v60, v76
	s_nop 0
	v_add_f32_e32 v75, v61, v75
	s_cbranch_scc1 .LBB0_410
	s_waitcnt lgkmcnt(0)
	s_barrier
	s_and_b64 vcc, exec, s[0:1]
	s_cbranch_vccnz .LBB0_410
	s_cmp_eq_u32 s64, -2
	s_waitcnt vmcnt(1)
	ds_write_b128 v193, v[66:69] offset:40960
	s_waitcnt vmcnt(0)
	ds_write_b128 v193, v[70:73] offset:51200
	s_cbranch_scc1 .LBB0_410
	s_cmp_lt_i32 s64, 3
	s_mov_b64 s[0:1], -1
	s_cbranch_scc1 .LBB0_407
	s_lshl_b32 s0, s65, 6
	s_add_i32 s0, s0, s3
	s_add_i32 s62, s0, 64
	s_mov_b64 s[0:1], 0

.LBB0_410:
	v_cvt_pk_bf16_f32 v110, v2, v3
	v_sub_f32_e32 v2, v118, v122
	v_exp_f32_e32 v2, v2
	v_cvt_pk_bf16_f32 v98, v6, v7
	v_sub_f32_e32 v6, v118, v125
	v_exp_f32_e32 v6, v6
	v_cndmask_b32_e64 v2, 0, v2, s[60:61]
	v_add_f32_e32 v231, v2, v114
	v_sub_f32_e32 v2, v118, v123
	v_exp_f32_e32 v2, v2
	v_sub_f32_e32 v76, v118, v124
	v_exp_f32_e32 v76, v76
	v_cndmask_b32_e64 v6, 0, v6, s[60:61]
	v_cndmask_b32_e64 v2, 0, v2, s[60:61]
	v_add_f32_e32 v197, v6, v75
	v_cvt_pk_bf16_f32 v111, v4, v5
	v_add_f32_e32 v230, v2, v131
	ds_read_b64_tr_b16 v[4:5], v222 offset:12800
	ds_read_b64_tr_b16 v[2:3], v222 offset:10240
	ds_read_b64_tr_b16 v[6:7], v222 offset:10272
	v_cndmask_b32_e64 v76, 0, v76, s[60:61]
	v_add_f32_e32 v228, v76, v74
	v_cvt_pk_bf16_f32 v114, v90, v91
	v_cvt_pk_bf16_f32 v115, v92, v93
	v_cvt_pk_bf16_f32 v116, v94, v95
	v_cvt_pk_bf16_f32 v117, v96, v97
	ds_read_b64_tr_b16 v[74:75], v222 offset:15360
	ds_read_b64_tr_b16 v[76:77], v222 offset:17920
	v_cvt_pk_bf16_f32 v99, v8, v9
	v_cvt_pk_bf16_f32 v112, v10, v11
	s_waitcnt lgkmcnt(3)
	v_mfma_f32_16x16x32_bf16 v[8:11], v[2:5], v[114:117], 0
	v_cvt_pk_bf16_f32 v101, v16, v17
	v_cvt_pk_bf16_f32 v16, v62, v63
	v_cvt_pk_bf16_f32 v17, v64, v65
	v_cvt_pk_bf16_f32 v62, v102, v103
	v_cvt_pk_bf16_f32 v63, v104, v105
	v_cvt_pk_bf16_f32 v64, v119, v120
	v_cvt_pk_bf16_f32 v65, v121, v126
	v_cvt_pk_bf16_f32 v100, v14, v15
	v_cvt_pk_bf16_f32 v113, v12, v13
	s_waitcnt lgkmcnt(0)
	v_mfma_f32_16x16x32_bf16 v[102:105], v[74:77], v[62:65], v[8:11]
	v_cvt_pk_bf16_f32 v118, v78, v79
	v_cvt_pk_bf16_f32 v119, v80, v81
	v_cvt_pk_bf16_f32 v120, v82, v83
	ds_read_b64_tr_b16 v[8:9], v222 offset:12832
	v_cvt_pk_bf16_f32 v121, v84, v85
	v_cvt_pk_bf16_f32 v14, v54, v55
	v_cvt_pk_bf16_f32 v15, v56, v57
	v_cvt_pk_bf16_f32 v106, v50, v51
	v_cvt_pk_bf16_f32 v107, v52, v53
	v_mfma_f32_16x16x32_bf16 v[50:53], v[2:5], v[118:121], 0
	v_cvt_pk_bf16_f32 v108, v58, v59
	v_cvt_pk_bf16_f32 v109, v60, v61
	v_cvt_pk_bf16_f32 v86, v86, v87
	v_mfma_f32_16x16x32_bf16 v[54:57], v[2:5], v[98:101], 0
	v_cvt_pk_bf16_f32 v87, v88, v89
	v_cvt_pk_bf16_f32 v88, v127, v128
	v_cvt_pk_bf16_f32 v89, v129, v130
	v_mfma_f32_16x16x32_bf16 v[2:5], v[2:5], v[110:113], 0
	ds_read_b64_tr_b16 v[78:79], v222 offset:15392
	ds_read_b64_tr_b16 v[80:81], v222 offset:17952
	s_add_i32 s88, s64, 3
	s_add_i32 s65, s65, -2
	v_mfma_f32_16x16x32_bf16 v[82:85], v[74:77], v[86:89], v[50:53]
	s_addk_i32 s68, 0x4000
	s_add_i32 s69, s64, 5
	s_mov_b32 s71, 1
	v_mfma_f32_16x16x32_bf16 v[58:61], v[74:77], v[14:17], v[54:57]
	v_lshl_add_u64 v[214:215], v[194:195], 0, s[74:75]
	s_sub_i32 s70, s2, s70
	s_mov_b32 s72, 4
	v_mfma_f32_16x16x32_bf16 v[10:13], v[74:77], v[106:109], v[2:5]
	s_waitcnt lgkmcnt(2)
	v_mfma_f32_16x16x32_bf16 v[2:5], v[6:9], v[114:117], 0
	v_mfma_f32_16x16x32_bf16 v[50:53], v[6:9], v[118:121], 0
	v_mfma_f32_16x16x32_bf16 v[54:57], v[6:9], v[98:101], 0
	v_mfma_f32_16x16x32_bf16 v[6:9], v[6:9], v[110:113], 0
	s_waitcnt lgkmcnt(0)
	v_mfma_f32_16x16x32_bf16 v[94:97], v[78:81], v[62:65], v[2:5]
	v_mfma_f32_16x16x32_bf16 v[2:5], v[78:81], v[106:109], v[6:9]
	s_nop 4
	ds_read_b64_tr_b16 v[6:7], v222 offset:10304
	ds_read_b64_tr_b16 v[8:9], v222 offset:12864
	ds_read_b64_tr_b16 v[130:131], v222 offset:15424
	ds_read_b64_tr_b16 v[132:133], v222 offset:17984
	v_mfma_f32_16x16x32_bf16 v[74:77], v[78:81], v[86:89], v[50:53]
	v_mfma_f32_16x16x32_bf16 v[50:53], v[78:81], v[14:17], v[54:57]
	s_waitcnt lgkmcnt(2)
	v_mfma_f32_16x16x32_bf16 v[54:57], v[6:9], v[114:117], 0
	v_mfma_f32_16x16x32_bf16 v[126:129], v[6:9], v[98:101], 0
	s_waitcnt lgkmcnt(0)
	v_mfma_f32_16x16x32_bf16 v[90:93], v[130:133], v[62:65], v[54:57]
	v_mfma_f32_16x16x32_bf16 v[54:57], v[130:133], v[14:17], v[126:129]
	s_nop 4
	ds_read_b64_tr_b16 v[126:127], v222 offset:10336
	ds_read_b64_tr_b16 v[128:129], v222 offset:12896
	v_mfma_f32_16x16x32_bf16 v[78:81], v[6:9], v[118:121], 0
	v_mfma_f32_16x16x32_bf16 v[6:9], v[6:9], v[110:113], 0
	v_mfma_f32_16x16x32_bf16 v[78:81], v[130:133], v[86:89], v[78:81]
	v_mfma_f32_16x16x32_bf16 v[6:9], v[130:133], v[106:109], v[6:9]
	s_waitcnt lgkmcnt(0)
	v_mfma_f32_16x16x32_bf16 v[114:117], v[126:129], v[114:117], 0
	v_mfma_f32_16x16x32_bf16 v[118:121], v[126:129], v[118:121], 0
	v_mfma_f32_16x16x32_bf16 v[130:133], v[126:129], v[98:101], 0
	v_mfma_f32_16x16x32_bf16 v[110:113], v[126:129], v[110:113], 0
	ds_read_b64_tr_b16 v[126:127], v222 offset:15456
	ds_read_b64_tr_b16 v[128:129], v222 offset:18016
	s_waitcnt lgkmcnt(0)
	v_mfma_f32_16x16x32_bf16 v[98:101], v[126:129], v[62:65], v[114:117]
	s_nop 2
	v_xor_b32_e32 v114, 0x80000000, v124
	v_mov_b32_e32 v115, v114
	v_mfma_f32_16x16x32_bf16 v[86:89], v[126:129], v[86:89], v[118:121]
	v_mov_b32_e32 v116, v114
	v_mov_b32_e32 v117, v114
	v_mfma_f32_16x16x32_bf16 v[62:65], v[126:129], v[14:17], v[130:133]
	v_xor_b32_e32 v118, 0x80000000, v125
	v_mov_b32_e32 v119, v118
	v_mov_b32_e32 v120, v118
	v_mfma_f32_16x16x32_bf16 v[14:17], v[126:129], v[106:109], v[110:113]
	v_xor_b32_e32 v106, 0x80000000, v122
	v_mov_b32_e32 v107, v106
	v_mov_b32_e32 v108, v106
	v_xor_b32_e32 v110, 0x80000000, v123
	v_mov_b32_e32 v109, v106
	v_mov_b32_e32 v111, v110
	v_mov_b32_e32 v112, v110
	v_mov_b32_e32 v113, v110
	v_mov_b32_e32 v121, v118
	s_branch .LBB0_412
.LBB0_411:
	v_cvt_pk_bf16_f32 v139, v132, v133
	v_cvt_pk_bf16_f32 v132, v162, v163
	v_add3_u32 v162, s73, v218, v221
	v_cvt_pk_bf16_f32 v124, v154, v155
	v_cvt_pk_bf16_f32 v125, v156, v157
	v_cvt_pk_bf16_f32 v126, v126, v127
	v_cvt_pk_bf16_f32 v127, v128, v129
	v_cvt_pk_bf16_f32 v128, v158, v159
	ds_read_b64_tr_b16 v[156:157], v162 offset:12800
	ds_read_b64_tr_b16 v[154:155], v162 offset:10240
	ds_read_b64_tr_b16 v[158:159], v162 offset:10272
	v_add_f32_e32 v228, v228, v138
	v_cvt_pk_bf16_f32 v138, v130, v131
	v_cvt_pk_bf16_f32 v140, v142, v143
	v_cvt_pk_bf16_f32 v141, v144, v145
	v_cvt_pk_bf16_f32 v122, v146, v147
	v_cvt_pk_bf16_f32 v123, v148, v149
	v_cvt_pk_bf16_f32 v142, v150, v151
	v_cvt_pk_bf16_f32 v143, v152, v153
	v_cvt_pk_bf16_f32 v144, v134, v135
	v_cvt_pk_bf16_f32 v145, v136, v137
	v_cvt_pk_bf16_f32 v146, v182, v183
	v_cvt_pk_bf16_f32 v147, v184, v185
	v_cvt_pk_bf16_f32 v148, v178, v179
	v_cvt_pk_bf16_f32 v149, v180, v181
	v_cvt_pk_bf16_f32 v150, v235, v236
	v_cvt_pk_bf16_f32 v151, v237, v239
	v_cvt_pk_bf16_f32 v152, v166, v167
	v_cvt_pk_bf16_f32 v153, v168, v169
	v_cvt_pk_bf16_f32 v129, v160, v161
	s_waitcnt lgkmcnt(1)
	v_mfma_f32_16x16x32_bf16 v[102:105], v[154:157], v[146:149], v[102:105]
	v_cvt_pk_bf16_f32 v134, v174, v175
	v_cvt_pk_bf16_f32 v135, v176, v177
	v_cvt_pk_bf16_f32 v136, v188, v232
	v_mfma_f32_16x16x32_bf16 v[82:85], v[154:157], v[150:153], v[82:85]
	v_cvt_pk_bf16_f32 v137, v233, v234
	v_cvt_pk_bf16_f32 v130, v240, v241
	v_cvt_pk_bf16_f32 v131, v242, v243
	v_mfma_f32_16x16x32_bf16 v[58:61], v[154:157], v[138:141], v[58:61]
	v_cvt_pk_bf16_f32 v133, v164, v165
	s_add_i32 s0, s71, 1
	s_cmp_lg_u32 s71, 2
	v_mfma_f32_16x16x32_bf16 v[10:13], v[154:157], v[142:145], v[10:13]
	ds_read_b64_tr_b16 v[154:155], v162 offset:15360
	ds_read_b64_tr_b16 v[156:157], v162 offset:17920
	ds_read_b64_tr_b16 v[160:161], v162 offset:12832
	s_cselect_b32 s71, s0, 0
	s_waitcnt lgkmcnt(1)
	v_mfma_f32_16x16x32_bf16 v[102:105], v[154:157], v[134:137], v[102:105]
	s_add_i32 s72, s72, 1
	s_add_i32 s0, s70, s72
	v_add_f32_e32 v197, v197, v170
	v_mfma_f32_16x16x32_bf16 v[82:85], v[154:157], v[130:133], v[82:85]
	v_add_f32_e32 v231, v231, v238
	v_add_f32_e32 v230, v230, v244
	s_cmp_eq_u32 s0, 8
	v_mfma_f32_16x16x32_bf16 v[58:61], v[154:157], v[122:125], v[58:61]
	v_mfma_f32_16x16x32_bf16 v[10:13], v[154:157], v[126:129], v[10:13]
	ds_read_b64_tr_b16 v[154:155], v162 offset:15392
	ds_read_b64_tr_b16 v[156:157], v162 offset:17952
	s_waitcnt lgkmcnt(2)
	v_mfma_f32_16x16x32_bf16 v[94:97], v[158:161], v[146:149], v[94:97]
	v_mfma_f32_16x16x32_bf16 v[74:77], v[158:161], v[150:153], v[74:77]
	v_mfma_f32_16x16x32_bf16 v[50:53], v[158:161], v[138:141], v[50:53]
	v_mfma_f32_16x16x32_bf16 v[2:5], v[158:161], v[142:145], v[2:5]
	s_waitcnt lgkmcnt(0)
	v_mfma_f32_16x16x32_bf16 v[94:97], v[154:157], v[134:137], v[94:97]
	v_mfma_f32_16x16x32_bf16 v[74:77], v[154:157], v[130:133], v[74:77]
	v_mfma_f32_16x16x32_bf16 v[50:53], v[154:157], v[122:125], v[50:53]
	v_mfma_f32_16x16x32_bf16 v[2:5], v[154:157], v[126:129], v[2:5]
	ds_read_b64_tr_b16 v[154:155], v162 offset:10304
	ds_read_b64_tr_b16 v[156:157], v162 offset:12864
	s_waitcnt lgkmcnt(0)
	v_mfma_f32_16x16x32_bf16 v[90:93], v[154:157], v[146:149], v[90:93]
	v_mfma_f32_16x16x32_bf16 v[78:81], v[154:157], v[150:153], v[78:81]
	v_mfma_f32_16x16x32_bf16 v[54:57], v[154:157], v[138:141], v[54:57]
	v_mfma_f32_16x16x32_bf16 v[6:9], v[154:157], v[142:145], v[6:9]
	ds_read_b64_tr_b16 v[154:155], v162 offset:15424
	ds_read_b64_tr_b16 v[156:157], v162 offset:17984
	s_waitcnt lgkmcnt(0)
	v_mfma_f32_16x16x32_bf16 v[90:93], v[154:157], v[134:137], v[90:93]
	v_mfma_f32_16x16x32_bf16 v[78:81], v[154:157], v[130:133], v[78:81]
	v_mfma_f32_16x16x32_bf16 v[54:57], v[154:157], v[122:125], v[54:57]
	v_mfma_f32_16x16x32_bf16 v[6:9], v[154:157], v[126:129], v[6:9]
	ds_read_b64_tr_b16 v[154:155], v162 offset:10336
	ds_read_b64_tr_b16 v[156:157], v162 offset:12896
	s_waitcnt lgkmcnt(0)
	v_mfma_f32_16x16x32_bf16 v[62:65], v[154:157], v[138:141], v[62:65]
	ds_read_b64_tr_b16 v[138:139], v162 offset:15456
	ds_read_b64_tr_b16 v[140:141], v162 offset:18016
	v_mfma_f32_16x16x32_bf16 v[98:101], v[154:157], v[146:149], v[98:101]
	v_mfma_f32_16x16x32_bf16 v[86:89], v[154:157], v[150:153], v[86:89]
	v_mfma_f32_16x16x32_bf16 v[14:17], v[154:157], v[142:145], v[14:17]
	s_waitcnt lgkmcnt(0)
	v_mfma_f32_16x16x32_bf16 v[98:101], v[138:141], v[134:137], v[98:101]
	v_mfma_f32_16x16x32_bf16 v[86:89], v[138:141], v[130:133], v[86:89]
	v_mfma_f32_16x16x32_bf16 v[62:65], v[138:141], v[122:125], v[62:65]
	v_mfma_f32_16x16x32_bf16 v[14:17], v[138:141], v[126:129], v[14:17]
	s_cbranch_scc1 .LBB0_368
.LBB0_412:
	s_andn2_b64 vcc, exec, s[66:67]
	s_add_i32 s74, s72, -3
	s_cbranch_vccnz .LBB0_416
	s_waitcnt lgkmcnt(0)
	s_barrier
	s_cmp_ge_i32 s74, s88
	s_cbranch_scc1 .LBB0_416
	s_mul_i32 s0, s71, 0x2800
	s_addk_i32 s0, 0xd800
	s_cmp_lg_u32 s71, 0
	s_cselect_b32 s0, s0, 0x5000
	v_lshl_add_u32 v122, s0, 1, v193
	s_cmp_ge_i32 s72, s69
	s_waitcnt vmcnt(1)
	ds_write_b128 v122, v[66:69]
	s_waitcnt vmcnt(0)
	ds_write_b128 v122, v[70:73] offset:10240
	s_cbranch_scc1 .LBB0_416
	s_cmp_gt_i32 s72, s64
	s_cselect_b32 s0, s89, s65
	s_cselect_b32 s1, s68, s3
	s_add_i32 s0, s0, s72
	s_lshl_b32 s0, s0, 6
	s_add_i32 s0, s0, s1
	v_add_u32_e32 v66, s0, v187
	v_mad_i64_i32 v[70:71], s[0:1], v66, s33, v[214:215]
	global_load_dwordx4 v[66:69], v[70:71], off offset:2048
	s_nop 0
	global_load_dwordx4 v[70:73], v[70:71], off offset:2304
.LBB0_416:
	s_add_i32 s73, s2, s72
	s_cmp_gt_i32 s74, s64
	s_cselect_b64 s[62:63], -1, 0
	s_cmp_lg_u32 s73, 3
	s_cselect_b64 s[0:1], -1, 0
	s_cmp_lg_u32 s73, 7
	s_mul_i32 s73, s71, 0x5000
	s_cselect_b64 s[76:77], -1, 0
	s_add_i32 s73, s73, 0
	v_add3_u32 v162, s73, v216, v224
	ds_read_b128 v[150:153], v162
	ds_read_b128 v[134:137], v162 offset:64
	s_waitcnt lgkmcnt(1)
	v_mfma_f32_16x16x32_bf16 v[122:125], v[150:153], v[18:21], v[106:109]
	ds_read_b128 v[138:141], v162 offset:2560
	ds_read_b128 v[126:129], v162 offset:2624
	s_and_b64 s[76:77], s[0:1], s[76:77]
	s_or_b64 s[92:93], s[62:63], s[76:77]
	s_waitcnt lgkmcnt(2)
	v_mfma_f32_16x16x32_bf16 v[182:185], v[134:137], v[22:25], v[122:125]
	s_and_b64 vcc, exec, s[92:93]
	v_cndmask_b32_e64 v245, 0, 1, s[6:7]
	v_cndmask_b32_e64 v246, 0, 1, s[4:5]
	v_mfma_f32_16x16x32_bf16 v[122:125], v[150:153], v[26:29], v[110:113]
	v_mfma_f32_16x16x32_bf16 v[158:161], v[134:137], v[30:33], v[122:125]
	s_waitcnt lgkmcnt(1)
	v_mfma_f32_16x16x32_bf16 v[122:125], v[138:141], v[18:21], v[106:109]
	s_waitcnt lgkmcnt(0)
	v_mfma_f32_16x16x32_bf16 v[178:181], v[126:129], v[22:25], v[122:125]
	v_mfma_f32_16x16x32_bf16 v[122:125], v[138:141], v[26:29], v[110:113]
	v_mfma_f32_16x16x32_bf16 v[166:169], v[126:129], v[30:33], v[122:125]
	s_nop 6
	v_add3_u32 v122, s73, v217, v224
	ds_read_b128 v[146:149], v122
	ds_read_b128 v[142:145], v122 offset:64
	s_waitcnt lgkmcnt(1)
	v_mfma_f32_16x16x32_bf16 v[122:125], v[146:149], v[18:21], v[106:109]
	s_waitcnt lgkmcnt(0)
	v_mfma_f32_16x16x32_bf16 v[174:177], v[142:145], v[22:25], v[122:125]
	v_mfma_f32_16x16x32_bf16 v[122:125], v[146:149], v[26:29], v[110:113]
	v_mfma_f32_16x16x32_bf16 v[154:157], v[142:145], v[30:33], v[122:125]
	ds_read_b128 v[130:133], v162 offset:7680
	s_nop 5
	ds_read_b128 v[122:125], v162 offset:7744
	s_waitcnt lgkmcnt(1)
	v_mfma_f32_16x16x32_bf16 v[162:165], v[130:133], v[18:21], v[106:109]
	s_waitcnt lgkmcnt(0)
	v_mfma_f32_16x16x32_bf16 v[170:173], v[122:125], v[22:25], v[162:165]
	v_mfma_f32_16x16x32_bf16 v[162:165], v[130:133], v[26:29], v[110:113]
	v_mfma_f32_16x16x32_bf16 v[162:165], v[122:125], v[30:33], v[162:165]
	s_cbranch_vccnz .LBB0_418
	v_cndmask_b32_e64 v188, v246, v245, s[0:1]
	v_and_b32_e32 v232, 1, v188
	v_mov_b32_e32 v188, s58
	v_cmp_eq_u32_e32 vcc, 1, v232
	v_cndmask_b32_e64 v232, 0, 1, s[8:9]
	v_cndmask_b32_e64 v161, v225, v161, s[0:1]
	v_cndmask_b32_e32 v182, v188, v182, vcc
	v_cndmask_b32_e64 v188, 0, 1, s[10:11]
	v_cndmask_b32_e64 v188, v232, v188, s[0:1]
	v_and_b32_e32 v188, 1, v188
	v_cmp_eq_u32_e64 s[62:63], 1, v188
	v_cndmask_b32_e64 v188, 0, 1, s[14:15]
	v_cndmask_b32_e64 v232, 0, 1, s[12:13]
	v_cndmask_b32_e64 v188, v232, v188, s[0:1]
	v_and_b32_e32 v188, 1, v188
	v_cndmask_b32_e64 v183, v225, v183, s[62:63]
	v_cmp_eq_u32_e64 s[62:63], 1, v188
	v_cndmask_b32_e64 v188, 0, 1, s[18:19]
	v_cndmask_b32_e64 v232, 0, 1, s[16:17]
	v_cndmask_b32_e64 v188, v232, v188, s[0:1]
	v_and_b32_e32 v188, 1, v188
	v_cndmask_b32_e64 v184, v225, v184, s[62:63]
	v_cmp_eq_u32_e64 s[62:63], 1, v188
	v_mov_b32_e32 v188, s58
	v_cndmask_b32_e32 v166, v188, v166, vcc
	v_cndmask_b32_e64 v188, 0, 1, s[22:23]
	v_cndmask_b32_e64 v232, 0, 1, s[20:21]
	v_cndmask_b32_e64 v188, v232, v188, s[0:1]
	v_and_b32_e32 v188, 1, v188
	v_cmp_eq_u32_e32 vcc, 1, v188
	v_cndmask_b32_e64 v188, 0, 1, s[26:27]
	v_cndmask_b32_e64 v232, 0, 1, s[24:25]
	v_cndmask_b32_e64 v188, v232, v188, s[0:1]
	v_and_b32_e32 v188, 1, v188
	v_cndmask_b32_e32 v167, v225, v167, vcc
	v_cmp_eq_u32_e32 vcc, 1, v188
	v_cndmask_b32_e64 v188, 0, 1, s[30:31]
	v_cndmask_b32_e64 v232, 0, 1, s[28:29]
	v_cndmask_b32_e64 v188, v232, v188, s[0:1]
	v_and_b32_e32 v188, 1, v188
	v_cndmask_b32_e32 v168, v225, v168, vcc
	v_cmp_eq_u32_e32 vcc, 1, v188
	v_cndmask_b32_e64 v185, v225, v185, s[62:63]
	v_cndmask_b32_e64 v160, v225, v160, s[0:1]
	v_cndmask_b32_e64 v159, v225, v159, s[0:1]
	v_cndmask_b32_e64 v158, v225, v158, s[0:1]
	v_cndmask_b32_e64 v181, v181, v225, s[0:1]
	v_cndmask_b32_e64 v180, v180, v225, s[0:1]
	v_cndmask_b32_e64 v179, v179, v225, s[0:1]
	v_cndmask_b32_e64 v178, v178, v225, s[0:1]
	v_cndmask_b32_e32 v169, v225, v169, vcc
	v_cndmask_b32_e64 v177, v177, v225, s[0:1]
	v_cndmask_b32_e64 v176, v176, v225, s[0:1]
	v_cndmask_b32_e64 v175, v175, v225, s[0:1]
	v_cndmask_b32_e64 v174, v174, v225, s[0:1]
	v_cndmask_b32_e64 v157, v157, v225, s[0:1]
	v_cndmask_b32_e64 v156, v156, v225, s[0:1]
	v_cndmask_b32_e64 v155, v155, v225, s[0:1]
	v_cndmask_b32_e64 v154, v154, v225, s[0:1]
	v_cndmask_b32_e64 v173, v173, v225, s[0:1]
	v_cndmask_b32_e64 v172, v172, v225, s[0:1]
	v_cndmask_b32_e64 v171, v171, v225, s[0:1]
	v_cndmask_b32_e64 v170, v170, v225, s[0:1]
	v_cndmask_b32_e64 v165, v165, v225, s[0:1]
	v_cndmask_b32_e64 v164, v164, v225, s[0:1]
	v_cndmask_b32_e64 v163, v163, v225, s[0:1]
	v_cndmask_b32_e64 v162, v162, v225, s[0:1]

.LBB0_420:
	s_nop 3
	v_exp_f32_e32 v130, v170
	v_exp_f32_e32 v131, v171
	v_exp_f32_e32 v132, v172
	v_exp_f32_e32 v133, v173
	v_add_f32_e32 v142, 0, v130
	v_exp_f32_e32 v150, v150
	v_add_f32_e32 v142, v131, v142
	v_exp_f32_e32 v151, v151
	v_add_f32_e32 v143, v132, v142
	v_exp_f32_e32 v142, v158
	v_exp_f32_e32 v152, v152
	v_add_f32_e32 v144, v133, v143
	v_exp_f32_e32 v143, v159
	v_exp_f32_e32 v153, v153
	v_add_f32_e32 v145, v142, v144
	v_exp_f32_e32 v144, v160
	v_exp_f32_e32 v134, v134
	v_add_f32_e32 v146, v143, v145
	v_exp_f32_e32 v145, v161
	v_exp_f32_e32 v135, v135
	v_add_f32_e32 v147, v144, v146
	v_exp_f32_e32 v146, v154
	v_exp_f32_e32 v136, v136
	v_add_f32_e32 v148, v145, v147
	v_exp_f32_e32 v147, v155
	v_exp_f32_e32 v137, v137
	v_add_f32_e32 v149, v146, v148
	v_exp_f32_e32 v148, v156
	v_exp_f32_e32 v126, v126
	v_add_f32_e32 v154, v147, v149
	v_exp_f32_e32 v149, v157
	v_exp_f32_e32 v127, v127
	v_add_f32_e32 v155, v148, v154
	v_exp_f32_e32 v154, v138
	v_add_f32_e32 v138, v149, v155
	v_exp_f32_e32 v155, v139
	v_add_f32_e32 v139, 0, v150
	v_exp_f32_e32 v128, v128
	v_add_f32_e32 v139, v151, v139
	v_exp_f32_e32 v129, v129
	v_add_f32_e32 v139, v152, v139
	v_exp_f32_e32 v158, v122
	v_add_f32_e32 v139, v153, v139
	v_exp_f32_e32 v159, v123
	v_add_f32_e32 v139, v134, v139
	v_add_f32_e32 v138, v154, v138
	v_add_f32_e32 v139, v135, v139
	v_exp_f32_e32 v156, v140
	v_add_f32_e32 v139, v136, v139
	v_exp_f32_e32 v160, v124
	v_add_f32_e32 v139, v137, v139
	v_add_f32_e32 v138, v155, v138
	v_add_f32_e32 v139, v126, v139
	v_exp_f32_e32 v157, v141
	v_add_f32_e32 v139, v127, v139
	v_exp_f32_e32 v161, v125
	v_add_f32_e32 v139, v128, v139
	s_andn2_b64 vcc, exec, s[94:95]
	v_add_f32_e32 v122, v129, v139
	v_add_f32_e32 v138, v156, v138
	v_add_f32_e32 v122, v158, v122
	s_nop 0
	v_add_f32_e32 v122, v159, v122
	v_add_f32_e32 v138, v157, v138
	v_add_f32_e32 v122, v160, v122
	s_nop 0
	v_add_f32_e32 v170, v161, v122
	s_cbranch_vccnz .LBB0_411
	s_waitcnt lgkmcnt(0)
	s_barrier
	s_cmp_ge_i32 s74, s88
	s_cbranch_scc1 .LBB0_411
	s_mul_i32 s0, s71, 0x2800
	s_addk_i32 s0, 0xd800
	s_cmp_lg_u32 s71, 0
	s_cselect_b32 s0, s0, 0x5000
	v_lshl_add_u32 v122, s0, 1, v193
	s_cmp_ge_i32 s72, s69
	s_waitcnt vmcnt(1)
	ds_write_b128 v122, v[66:69]
	s_waitcnt vmcnt(0)
	ds_write_b128 v122, v[70:73] offset:10240
	s_cbranch_scc1 .LBB0_411
	s_cmp_gt_i32 s72, s64
	s_cselect_b32 s0, s89, s65
	s_cselect_b32 s1, s68, s3
	s_add_i32 s0, s0, s72
	s_lshl_b32 s0, s0, 6
	s_add_i32 s0, s0, s1
	v_add_u32_e32 v66, s0, v187
	v_mad_i64_i32 v[70:71], s[0:1], v66, s33, v[214:215]
	global_load_dwordx4 v[66:69], v[70:71], off offset:2048
	s_nop 0
	global_load_dwordx4 v[70:73], v[70:71], off offset:2304
	s_branch .LBB0_411
